# GLU epilogue: waits on the hoisted loads use in-order counts that admit younger stores and row-sum atomics (no wait on the previous sub-step's stores/atomic); on top of v71
# baseline (speedup 1.0000x reference)
.LBB0_227:
	v_lshl_add_u32 v140, s80, 8, v146
	s_movk_i32 s2, 0x1fff
	v_cmp_lt_i32_e32 vcc, s2, v140
	s_and_saveexec_b64 s[2:3], vcc
	s_xor_b64 s[2:3], exec, s[2:3]
	v_add_u32_e32 v134, 0xffffe000, v140
	v_lshlrev_b64 v[142:143], 14, v[134:135]
	v_mov_b32_e32 v141, v135
	v_lshl_add_u64 v[142:143], s[10:11], 0, v[142:143]
	v_mov_b64_e32 v[144:145], v[140:141]
	s_or_saveexec_b64 s[2:3], s[2:3]
	v_ashrrev_i32_e32 v141, 31, v140
	s_xor_b64 exec, exec, s[2:3]
	v_lshlrev_b64 v[142:143], 14, v[140:141]
	v_lshl_add_u64 v[142:143], s[8:9], 0, v[142:143]
	v_mov_b64_e32 v[144:145], v[140:141]
	s_or_b64 exec, exec, s[2:3]
	v_lshl_or_b32 v160, s78, 7, v148
	v_ashrrev_i32_e32 v161, 31, v160
	v_lshlrev_b64 v[162:163], 2, v[160:161]
	v_lshl_add_u64 v[142:143], v[142:143], 0, v[162:163]
	global_load_dwordx4 v[170:173], v[142:143], off
	global_load_dwordx4 v[174:177], v[142:143], off offset:64
	v_lshl_add_u64 v[234:235], v[142:143], 0, s[38:39]
	global_load_dwordx4 v[178:181], v[234:235], off
	global_load_dwordx4 v[182:185], v[234:235], off offset:64
	v_lshl_add_u64 v[234:235], v[142:143], 0, s[40:41]
	global_load_dwordx4 v[186:189], v[234:235], off
	global_load_dwordx4 v[190:193], v[234:235], off offset:64
	v_lshl_add_u64 v[234:235], v[142:143], 0, s[42:43]
	global_load_dwordx4 v[194:197], v[234:235], off
	global_load_dwordx4 v[198:201], v[234:235], off offset:64
	v_lshl_add_u64 v[234:235], v[142:143], 0, s[44:45]
	global_load_dwordx4 v[202:205], v[234:235], off
	global_load_dwordx4 v[206:209], v[234:235], off offset:64
	v_lshl_add_u64 v[234:235], v[142:143], 0, s[46:47]
	global_load_dwordx4 v[210:213], v[234:235], off
	global_load_dwordx4 v[214:217], v[234:235], off offset:64
	v_lshl_add_u64 v[234:235], v[142:143], 0, s[48:49]
	global_load_dwordx4 v[218:221], v[234:235], off
	global_load_dwordx4 v[222:225], v[234:235], off offset:64
	v_lshl_add_u64 v[234:235], v[142:143], 0, s[66:67]
	global_load_dwordx4 v[226:229], v[234:235], off
	global_load_dwordx4 v[230:233], v[234:235], off offset:64
	v_lshlrev_b64 v[164:165], 14, v[144:145]
	v_mul_f32_e32 v134, 0xbfb8aa3b, v126
	v_mul_f32_e32 v153, 0xbfb8aa3b, v127
	v_mul_f32_e32 v155, 0xbfb8aa3b, v128
	v_mul_f32_e32 v168, 0xbfb8aa3b, v129
	v_lshl_add_u64 v[128:129], s[12:13], 0, v[164:165]
	v_exp_f32_e32 v134, v134
	v_exp_f32_e32 v153, v153
	v_exp_f32_e32 v155, v155
	v_exp_f32_e32 v164, v168
	v_lshlrev_b64 v[166:167], 13, v[144:145]
	v_lshl_add_u64 v[126:127], s[14:15], 0, v[166:167]
	v_add_f32_e32 v134, 1.0, v134
	v_add_f32_e32 v153, 1.0, v153
	v_add_f32_e32 v155, 1.0, v155
	v_add_f32_e32 v167, 1.0, v164
	v_rcp_f32_e32 v164, v134
	v_rcp_f32_e32 v165, v153
	v_rcp_f32_e32 v166, v155
	v_rcp_f32_e32 v167, v167
	v_lshl_add_u64 v[126:127], v[160:161], 1, v[126:127]
	v_lshl_add_u64 v[128:129], v[128:129], 0, v[162:163]
	v_mul_f32_e32 v118, 0xbfb8aa3b, v118
	v_mul_f32_e32 v119, 0xbfb8aa3b, v119
	v_mul_f32_e32 v120, 0xbfb8aa3b, v120
	v_mul_f32_e32 v121, 0xbfb8aa3b, v121
	v_exp_f32_e32 v155, v118
	v_exp_f32_e32 v119, v119
	v_and_b32_e32 v153, 64, v152
	v_exp_f32_e32 v120, v120
	v_exp_f32_e32 v121, v121
	v_xor_b32_e32 v134, 16, v152
	v_add_u32_e32 v153, 64, v153
	v_cmp_lt_i32_e32 vcc, v134, v153
	v_add_f32_e32 v119, 1.0, v119
	v_add_f32_e32 v161, 1.0, v121
	v_cndmask_b32_e32 v118, v152, v134, vcc
	v_add_f32_e32 v134, 1.0, v155
	v_add_f32_e32 v155, 1.0, v120
	v_rcp_f32_e32 v120, v134
	v_rcp_f32_e32 v121, v119
	v_rcp_f32_e32 v160, v155
	v_rcp_f32_e32 v161, v161
	v_lshlrev_b32_e32 v118, 2, v118
	s_waitcnt vmcnt(15)
	v_mov_b64_e32 v[156:157], v[170:171]
	v_mov_b64_e32 v[158:159], v[172:173]
	v_pk_fma_f32 v[122:123], v[122:123], v[164:165], v[156:157]
	v_pk_fma_f32 v[124:125], v[124:125], v[166:167], v[158:159]
	global_store_dwordx4 v[128:129], v[122:125], off
	v_cvt_pk_bf16_f32 v156, v122, v123
	v_cvt_pk_bf16_f32 v157, v124, v125
	global_store_dwordx2 v[126:127], v[156:157], off
	s_nop 0
	v_fma_f32 v119, v122, v122, 0
	v_fmac_f32_e32 v119, v123, v123
	v_fmac_f32_e32 v119, v124, v124
	v_fmac_f32_e32 v119, v125, v125
	s_waitcnt vmcnt(16)
	v_mov_b64_e32 v[156:157], v[174:175]
	v_mov_b64_e32 v[158:159], v[176:177]
	v_pk_fma_f32 v[120:121], v[114:115], v[120:121], v[156:157]
	s_nop 0
	v_fmac_f32_e32 v119, v120, v120
	v_pk_fma_f32 v[122:123], v[116:117], v[160:161], v[158:159]
	v_fmac_f32_e32 v119, v121, v121
	v_fmac_f32_e32 v119, v122, v122
	v_fmac_f32_e32 v119, v123, v123
	ds_bpermute_b32 v114, v118, v119
	v_xor_b32_e32 v115, 32, v152
	v_cmp_lt_i32_e32 vcc, v115, v153
	global_store_dwordx4 v[128:129], v[120:123], off offset:64
	s_nop 0
	v_cndmask_b32_e32 v116, v152, v115, vcc
	s_waitcnt lgkmcnt(0)
	v_add_f32_e32 v115, v119, v114
	v_lshlrev_b32_e32 v114, 2, v116
	ds_bpermute_b32 v116, v114, v115
	v_cvt_pk_bf16_f32 v120, v120, v121
	v_cvt_pk_bf16_f32 v121, v122, v123
	global_store_dwordx2 v[126:127], v[120:121], off offset:32
	s_and_saveexec_b64 s[2:3], s[0:1]
	s_mov_b32 s87, s93
	s_nop 0
	v_lshl_add_u64 v[120:121], v[144:145], 2, s[4:5]
	s_waitcnt lgkmcnt(0)
	v_add_f32_e32 v115, v115, v116
	global_atomic_add_f32 v[120:121], v115, off
.LBB0_233:
	s_or_b64 exec, exec, s[2:3]
	s_waitcnt lgkmcnt(0)
	v_add_co_u32_e32 v116, vcc, 0x40000, v142
	v_mul_f32_e32 v115, 0xbfb8aa3b, v110
	s_nop 0
	v_addc_co_u32_e32 v117, vcc, 0, v143, vcc
	s_nop 0
	v_mul_f32_e32 v119, 0xbfb8aa3b, v111
	v_mul_f32_e32 v112, 0xbfb8aa3b, v112
	v_mul_f32_e32 v113, 0xbfb8aa3b, v113
	v_exp_f32_e32 v115, v115
	v_exp_f32_e32 v119, v119
	v_exp_f32_e32 v112, v112
	v_exp_f32_e32 v113, v113
	v_add_f32_e32 v115, 1.0, v115
	v_add_f32_e32 v119, 1.0, v119
	v_add_f32_e32 v124, 1.0, v112
	v_add_f32_e32 v125, 1.0, v113
	v_rcp_f32_e32 v112, v115
	v_rcp_f32_e32 v113, v119
	v_rcp_f32_e32 v124, v124
	v_rcp_f32_e32 v125, v125
	v_add_co_u32_e32 v110, vcc, s79, v128
	s_mov_b32 s2, 0x20000
	s_nop 0
	v_addc_co_u32_e32 v111, vcc, 0, v129, vcc
	v_add_co_u32_e32 v144, vcc, s2, v126
	v_lshl_add_u64 v[116:117], v[142:143], 0, s[38:39]
	s_nop 0
	v_addc_co_u32_e32 v145, vcc, 0, v127, vcc
	v_mul_f32_e32 v98, 0xbfb8aa3b, v98
	v_mul_f32_e32 v99, 0xbfb8aa3b, v99
	v_exp_f32_e32 v98, v98
	v_exp_f32_e32 v99, v99
	v_mul_f32_e32 v100, 0xbfb8aa3b, v100
	v_mul_f32_e32 v101, 0xbfb8aa3b, v101
	v_exp_f32_e32 v100, v100
	v_exp_f32_e32 v101, v101
	v_add_f32_e32 v98, 1.0, v98
	v_add_f32_e32 v99, 1.0, v99
	v_rcp_f32_e32 v98, v98
	v_rcp_f32_e32 v99, v99
	v_add_f32_e32 v100, 1.0, v100
	v_add_f32_e32 v101, 1.0, v101
	s_mov_b64 s[2:3], 0x20000
	s_waitcnt vmcnt(18)
	v_mov_b64_e32 v[120:121], v[178:179]
	v_mov_b64_e32 v[122:123], v[180:181]
	v_pk_fma_f32 v[106:107], v[106:107], v[112:113], v[120:121]
	v_pk_fma_f32 v[108:109], v[108:109], v[124:125], v[122:123]
	global_store_dwordx4 v[110:111], v[106:109], off
	v_cvt_pk_bf16_f32 v110, v106, v107
	v_cvt_pk_bf16_f32 v111, v108, v109
	global_store_dwordx2 v[144:145], v[110:111], off
	s_nop 0
	v_fma_f32 v115, v106, v106, 0
	v_rcp_f32_e32 v116, v100
	v_rcp_f32_e32 v117, v101
	v_fmac_f32_e32 v115, v107, v107
	v_fmac_f32_e32 v115, v108, v108
	v_fmac_f32_e32 v115, v109, v109
	v_lshl_add_u64 v[106:107], v[126:127], 0, s[2:3]
	s_waitcnt vmcnt(19)
	v_mov_b64_e32 v[110:111], v[182:183]
	v_mov_b64_e32 v[112:113], v[184:185]
	v_pk_fma_f32 v[100:101], v[102:103], v[98:99], v[110:111]
	s_nop 0
	v_fmac_f32_e32 v115, v100, v100
	v_fmac_f32_e32 v115, v101, v101
	v_pk_fma_f32 v[102:103], v[104:105], v[116:117], v[112:113]
	v_lshl_add_u64 v[104:105], v[128:129], 0, s[38:39]
	v_fmac_f32_e32 v115, v102, v102
	v_fmac_f32_e32 v115, v103, v103
	ds_bpermute_b32 v98, v118, v115
	global_store_dwordx4 v[104:105], v[100:103], off offset:64
	s_waitcnt lgkmcnt(0)
	v_add_f32_e32 v98, v115, v98
	ds_bpermute_b32 v99, v114, v98
	v_cvt_pk_bf16_f32 v100, v100, v101
	v_cvt_pk_bf16_f32 v101, v102, v103
	global_store_dwordx2 v[106:107], v[100:101], off offset:32
	s_and_saveexec_b64 s[2:3], s[0:1]
	s_nop 0
	v_lshl_add_u64 v[100:101], v[140:141], 2, s[4:5]
	s_waitcnt lgkmcnt(0)
	v_add_f32_e32 v98, v98, v99
	global_atomic_add_f32 v[100:101], v98, off offset:64
.LBB0_235:
	s_or_b64 exec, exec, s[2:3]
	v_add_co_u32_e32 v98, vcc, 0x80000, v142
	v_mul_f32_e32 v104, 0xbfb8aa3b, v94
	s_waitcnt lgkmcnt(0)
	v_addc_co_u32_e32 v99, vcc, 0, v143, vcc
	s_nop 0
	v_mul_f32_e32 v105, 0xbfb8aa3b, v95
	v_mul_f32_e32 v96, 0xbfb8aa3b, v96
	v_mul_f32_e32 v97, 0xbfb8aa3b, v97
	v_exp_f32_e32 v104, v104
	v_exp_f32_e32 v105, v105
	v_exp_f32_e32 v96, v96
	v_exp_f32_e32 v97, v97
	v_add_f32_e32 v104, 1.0, v104
	v_add_f32_e32 v105, 1.0, v105
	v_add_f32_e32 v106, 1.0, v96
	v_add_f32_e32 v107, 1.0, v97
	s_mov_b32 s2, 0x80000
	v_rcp_f32_e32 v96, v104
	v_rcp_f32_e32 v97, v105
	v_rcp_f32_e32 v104, v106
	v_rcp_f32_e32 v105, v107
	v_add_co_u32_e32 v94, vcc, s2, v128
	v_lshl_add_u64 v[102:103], v[142:143], 0, s[40:41]
	s_nop 0
	v_addc_co_u32_e32 v95, vcc, 0, v129, vcc
	v_add_co_u32_e32 v106, vcc, s79, v126
	v_mul_f32_e32 v82, 0xbfb8aa3b, v82
	s_nop 0
	v_addc_co_u32_e32 v107, vcc, 0, v127, vcc
	v_mul_f32_e32 v83, 0xbfb8aa3b, v83
	v_exp_f32_e32 v82, v82
	v_exp_f32_e32 v83, v83
	v_mul_f32_e32 v84, 0xbfb8aa3b, v84
	v_mul_f32_e32 v85, 0xbfb8aa3b, v85
	v_exp_f32_e32 v84, v84
	v_exp_f32_e32 v85, v85
	v_add_f32_e32 v82, 1.0, v82
	v_add_f32_e32 v83, 1.0, v83
	v_rcp_f32_e32 v82, v82
	v_rcp_f32_e32 v83, v83
	v_add_f32_e32 v84, 1.0, v84
	v_add_f32_e32 v85, 1.0, v85
	s_waitcnt vmcnt(21)
	v_mov_b64_e32 v[98:99], v[186:187]
	v_mov_b64_e32 v[100:101], v[188:189]
	v_pk_fma_f32 v[90:91], v[90:91], v[96:97], v[98:99]
	v_pk_fma_f32 v[92:93], v[92:93], v[104:105], v[100:101]
	global_store_dwordx4 v[94:95], v[90:93], off
	v_cvt_pk_bf16_f32 v94, v90, v91
	v_cvt_pk_bf16_f32 v95, v92, v93
	global_store_dwordx2 v[106:107], v[94:95], off
	s_nop 0
	v_fma_f32 v100, v90, v90, 0
	v_rcp_f32_e32 v98, v84
	v_rcp_f32_e32 v99, v85
	v_fmac_f32_e32 v100, v91, v91
	v_fmac_f32_e32 v100, v92, v92
	v_fmac_f32_e32 v100, v93, v93
	v_lshl_add_u64 v[90:91], v[126:127], 0, s[38:39]
	s_waitcnt vmcnt(22)
	v_mov_b64_e32 v[94:95], v[190:191]
	v_mov_b64_e32 v[96:97], v[192:193]
	v_pk_fma_f32 v[84:85], v[86:87], v[82:83], v[94:95]
	s_nop 0
	v_fmac_f32_e32 v100, v84, v84
	v_fmac_f32_e32 v100, v85, v85
	v_pk_fma_f32 v[86:87], v[88:89], v[98:99], v[96:97]
	v_lshl_add_u64 v[88:89], v[128:129], 0, s[40:41]
	v_fmac_f32_e32 v100, v86, v86
	v_fmac_f32_e32 v100, v87, v87
	ds_bpermute_b32 v82, v118, v100
	global_store_dwordx4 v[88:89], v[84:87], off offset:64
	s_waitcnt lgkmcnt(0)
	v_add_f32_e32 v82, v100, v82
	ds_bpermute_b32 v83, v114, v82
	v_cvt_pk_bf16_f32 v84, v84, v85
	v_cvt_pk_bf16_f32 v85, v86, v87
	global_store_dwordx2 v[90:91], v[84:85], off offset:32
	s_and_saveexec_b64 s[2:3], s[0:1]
	s_nop 0
	v_lshl_add_u64 v[84:85], v[140:141], 2, s[4:5]
	s_waitcnt lgkmcnt(0)
	v_add_f32_e32 v82, v82, v83
	global_atomic_add_f32 v[84:85], v82, off offset:128
.LBB0_237:
	s_or_b64 exec, exec, s[2:3]
	v_add_co_u32_e32 v82, vcc, 0xc0000, v142
	v_mul_f32_e32 v88, 0xbfb8aa3b, v78
	s_waitcnt lgkmcnt(0)
	v_addc_co_u32_e32 v83, vcc, 0, v143, vcc
	s_nop 0
	v_mul_f32_e32 v89, 0xbfb8aa3b, v79
	v_mul_f32_e32 v80, 0xbfb8aa3b, v80
	v_mul_f32_e32 v81, 0xbfb8aa3b, v81
	v_exp_f32_e32 v88, v88
	v_exp_f32_e32 v89, v89
	v_exp_f32_e32 v80, v80
	v_exp_f32_e32 v81, v81
	v_add_f32_e32 v88, 1.0, v88
	v_add_f32_e32 v89, 1.0, v89
	v_add_f32_e32 v90, 1.0, v80
	v_add_f32_e32 v91, 1.0, v81
	s_mov_b32 s2, 0xc0000
	v_rcp_f32_e32 v80, v88
	v_rcp_f32_e32 v81, v89
	v_rcp_f32_e32 v88, v90
	v_rcp_f32_e32 v89, v91
	v_add_co_u32_e32 v78, vcc, s2, v128
	s_mov_b32 s2, 0x60000
	s_nop 0
	v_addc_co_u32_e32 v79, vcc, 0, v129, vcc
	v_add_co_u32_e32 v90, vcc, s2, v126
	v_lshl_add_u64 v[86:87], v[142:143], 0, s[42:43]
	s_nop 0
	v_addc_co_u32_e32 v91, vcc, 0, v127, vcc
	v_mul_f32_e32 v66, 0xbfb8aa3b, v66
	v_mul_f32_e32 v67, 0xbfb8aa3b, v67
	v_exp_f32_e32 v66, v66
	v_exp_f32_e32 v67, v67
	v_mul_f32_e32 v68, 0xbfb8aa3b, v68
	v_mul_f32_e32 v69, 0xbfb8aa3b, v69
	v_exp_f32_e32 v68, v68
	v_exp_f32_e32 v69, v69
	v_add_f32_e32 v66, 1.0, v66
	v_add_f32_e32 v67, 1.0, v67
	v_rcp_f32_e32 v66, v66
	v_rcp_f32_e32 v67, v67
	v_add_f32_e32 v68, 1.0, v68
	v_add_f32_e32 v69, 1.0, v69
	s_mov_b64 s[2:3], 0x60000
	s_waitcnt vmcnt(24)
	v_mov_b64_e32 v[82:83], v[194:195]
	v_mov_b64_e32 v[84:85], v[196:197]
	v_pk_fma_f32 v[74:75], v[74:75], v[80:81], v[82:83]
	v_pk_fma_f32 v[76:77], v[76:77], v[88:89], v[84:85]
	global_store_dwordx4 v[78:79], v[74:77], off
	v_cvt_pk_bf16_f32 v78, v74, v75
	v_cvt_pk_bf16_f32 v79, v76, v77
	global_store_dwordx2 v[90:91], v[78:79], off
	s_nop 0
	v_fma_f32 v84, v74, v74, 0
	v_rcp_f32_e32 v82, v68
	v_rcp_f32_e32 v83, v69
	v_fmac_f32_e32 v84, v75, v75
	v_fmac_f32_e32 v84, v76, v76
	v_fmac_f32_e32 v84, v77, v77
	v_lshl_add_u64 v[74:75], v[126:127], 0, s[2:3]
	s_waitcnt vmcnt(25)
	v_mov_b64_e32 v[78:79], v[198:199]
	v_mov_b64_e32 v[80:81], v[200:201]
	v_pk_fma_f32 v[68:69], v[70:71], v[66:67], v[78:79]
	s_nop 0
	v_fmac_f32_e32 v84, v68, v68
	v_fmac_f32_e32 v84, v69, v69
	v_pk_fma_f32 v[70:71], v[72:73], v[82:83], v[80:81]
	v_lshl_add_u64 v[72:73], v[128:129], 0, s[42:43]
	v_fmac_f32_e32 v84, v70, v70
	v_fmac_f32_e32 v84, v71, v71
	ds_bpermute_b32 v66, v118, v84
	global_store_dwordx4 v[72:73], v[68:71], off offset:64
	s_waitcnt lgkmcnt(0)
	v_add_f32_e32 v66, v84, v66
	ds_bpermute_b32 v67, v114, v66
	v_cvt_pk_bf16_f32 v68, v68, v69
	v_cvt_pk_bf16_f32 v69, v70, v71
	global_store_dwordx2 v[74:75], v[68:69], off offset:32
	s_and_saveexec_b64 s[2:3], s[0:1]
	s_nop 0
	v_lshl_add_u64 v[68:69], v[140:141], 2, s[4:5]
	s_waitcnt lgkmcnt(0)
	v_add_f32_e32 v66, v66, v67
	global_atomic_add_f32 v[68:69], v66, off offset:192
.LBB0_239:
	s_or_b64 exec, exec, s[2:3]
	v_add_co_u32_e32 v66, vcc, 0x200000, v142
	v_mul_f32_e32 v72, 0xbfb8aa3b, v62
	s_waitcnt lgkmcnt(0)
	v_addc_co_u32_e32 v67, vcc, 0, v143, vcc
	s_nop 0
	v_mul_f32_e32 v73, 0xbfb8aa3b, v63
	v_mul_f32_e32 v64, 0xbfb8aa3b, v64
	v_mul_f32_e32 v65, 0xbfb8aa3b, v65
	v_exp_f32_e32 v72, v72
	v_exp_f32_e32 v73, v73
	v_exp_f32_e32 v64, v64
	v_exp_f32_e32 v65, v65
	v_add_f32_e32 v72, 1.0, v72
	v_add_f32_e32 v73, 1.0, v73
	v_add_f32_e32 v74, 1.0, v64
	v_add_f32_e32 v75, 1.0, v65
	s_mov_b32 s2, 0x200000
	v_rcp_f32_e32 v64, v72
	v_rcp_f32_e32 v65, v73
	v_rcp_f32_e32 v72, v74
	v_rcp_f32_e32 v73, v75
	v_add_co_u32_e32 v62, vcc, s2, v128
	s_mov_b32 s2, 0x100000
	s_nop 0
	v_addc_co_u32_e32 v63, vcc, 0, v129, vcc
	v_add_co_u32_e32 v74, vcc, s2, v126
	v_lshl_add_u64 v[70:71], v[142:143], 0, s[44:45]
	s_nop 0
	v_addc_co_u32_e32 v75, vcc, 0, v127, vcc
	v_mul_f32_e32 v50, 0xbfb8aa3b, v50
	v_mul_f32_e32 v51, 0xbfb8aa3b, v51
	v_exp_f32_e32 v50, v50
	v_exp_f32_e32 v51, v51
	v_mul_f32_e32 v52, 0xbfb8aa3b, v52
	v_mul_f32_e32 v53, 0xbfb8aa3b, v53
	v_exp_f32_e32 v52, v52
	v_exp_f32_e32 v53, v53
	v_add_f32_e32 v50, 1.0, v50
	v_add_f32_e32 v51, 1.0, v51
	v_rcp_f32_e32 v50, v50
	v_rcp_f32_e32 v51, v51
	v_add_f32_e32 v52, 1.0, v52
	v_add_f32_e32 v53, 1.0, v53
	s_mov_b64 s[2:3], 0x100000
	s_waitcnt vmcnt(27)
	v_mov_b64_e32 v[66:67], v[202:203]
	v_mov_b64_e32 v[68:69], v[204:205]
	v_pk_fma_f32 v[58:59], v[58:59], v[64:65], v[66:67]
	v_pk_fma_f32 v[60:61], v[60:61], v[72:73], v[68:69]
	global_store_dwordx4 v[62:63], v[58:61], off
	v_cvt_pk_bf16_f32 v62, v58, v59
	v_cvt_pk_bf16_f32 v63, v60, v61
	global_store_dwordx2 v[74:75], v[62:63], off
	s_nop 0
	v_fma_f32 v68, v58, v58, 0
	v_rcp_f32_e32 v66, v52
	v_rcp_f32_e32 v67, v53
	v_fmac_f32_e32 v68, v59, v59
	v_fmac_f32_e32 v68, v60, v60
	v_fmac_f32_e32 v68, v61, v61
	v_lshl_add_u64 v[58:59], v[126:127], 0, s[2:3]
	s_waitcnt vmcnt(28)
	v_mov_b64_e32 v[62:63], v[206:207]
	v_mov_b64_e32 v[64:65], v[208:209]
	v_pk_fma_f32 v[52:53], v[54:55], v[50:51], v[62:63]
	s_nop 0
	v_fmac_f32_e32 v68, v52, v52
	v_fmac_f32_e32 v68, v53, v53
	v_pk_fma_f32 v[54:55], v[56:57], v[66:67], v[64:65]
	v_lshl_add_u64 v[56:57], v[128:129], 0, s[44:45]
	v_fmac_f32_e32 v68, v54, v54
	v_fmac_f32_e32 v68, v55, v55
	ds_bpermute_b32 v50, v118, v68
	global_store_dwordx4 v[56:57], v[52:55], off offset:64
	s_waitcnt lgkmcnt(0)
	v_add_f32_e32 v50, v68, v50
	ds_bpermute_b32 v51, v114, v50
	v_cvt_pk_bf16_f32 v52, v52, v53
	v_cvt_pk_bf16_f32 v53, v54, v55
	global_store_dwordx2 v[58:59], v[52:53], off offset:32
	s_and_saveexec_b64 s[2:3], s[0:1]
	s_nop 0
	v_lshl_add_u64 v[52:53], v[140:141], 2, s[4:5]
	s_waitcnt lgkmcnt(0)
	v_add_f32_e32 v50, v50, v51
	global_atomic_add_f32 v[52:53], v50, off offset:512
.LBB0_241:
	s_or_b64 exec, exec, s[2:3]
	v_add_co_u32_e32 v50, vcc, 0x240000, v142
	v_mul_f32_e32 v56, 0xbfb8aa3b, v46
	s_waitcnt lgkmcnt(0)
	v_addc_co_u32_e32 v51, vcc, 0, v143, vcc
	s_nop 0
	v_mul_f32_e32 v57, 0xbfb8aa3b, v47
	v_mul_f32_e32 v48, 0xbfb8aa3b, v48
	v_mul_f32_e32 v49, 0xbfb8aa3b, v49
	v_exp_f32_e32 v56, v56
	v_exp_f32_e32 v57, v57
	v_exp_f32_e32 v48, v48
	v_exp_f32_e32 v49, v49
	v_add_f32_e32 v56, 1.0, v56
	v_add_f32_e32 v57, 1.0, v57
	v_add_f32_e32 v58, 1.0, v48
	v_add_f32_e32 v59, 1.0, v49
	s_mov_b32 s2, 0x240000
	v_rcp_f32_e32 v48, v56
	v_rcp_f32_e32 v49, v57
	v_rcp_f32_e32 v56, v58
	v_rcp_f32_e32 v57, v59
	v_add_co_u32_e32 v46, vcc, s2, v128
	s_mov_b32 s2, 0x120000
	s_nop 0
	v_addc_co_u32_e32 v47, vcc, 0, v129, vcc
	v_add_co_u32_e32 v58, vcc, s2, v126
	v_lshl_add_u64 v[54:55], v[142:143], 0, s[46:47]
	s_nop 0
	v_addc_co_u32_e32 v59, vcc, 0, v127, vcc
	v_mul_f32_e32 v34, 0xbfb8aa3b, v34
	v_mul_f32_e32 v35, 0xbfb8aa3b, v35
	v_exp_f32_e32 v34, v34
	v_exp_f32_e32 v35, v35
	v_mul_f32_e32 v36, 0xbfb8aa3b, v36
	v_mul_f32_e32 v37, 0xbfb8aa3b, v37
	v_exp_f32_e32 v36, v36
	v_exp_f32_e32 v37, v37
	v_add_f32_e32 v34, 1.0, v34
	v_add_f32_e32 v35, 1.0, v35
	v_rcp_f32_e32 v34, v34
	v_rcp_f32_e32 v35, v35
	v_add_f32_e32 v36, 1.0, v36
	v_add_f32_e32 v37, 1.0, v37
	s_mov_b64 s[2:3], 0x120000
	s_waitcnt vmcnt(30)
	v_mov_b64_e32 v[50:51], v[210:211]
	v_mov_b64_e32 v[52:53], v[212:213]
	v_pk_fma_f32 v[42:43], v[42:43], v[48:49], v[50:51]
	v_pk_fma_f32 v[44:45], v[44:45], v[56:57], v[52:53]
	global_store_dwordx4 v[46:47], v[42:45], off
	v_cvt_pk_bf16_f32 v46, v42, v43
	v_cvt_pk_bf16_f32 v47, v44, v45
	global_store_dwordx2 v[58:59], v[46:47], off
	s_nop 0
	v_fma_f32 v52, v42, v42, 0
	v_rcp_f32_e32 v50, v36
	v_rcp_f32_e32 v51, v37
	v_fmac_f32_e32 v52, v43, v43
	v_fmac_f32_e32 v52, v44, v44
	v_fmac_f32_e32 v52, v45, v45
	v_lshl_add_u64 v[42:43], v[126:127], 0, s[2:3]
	s_waitcnt vmcnt(31)
	v_mov_b64_e32 v[46:47], v[214:215]
	v_mov_b64_e32 v[48:49], v[216:217]
	v_pk_fma_f32 v[36:37], v[38:39], v[34:35], v[46:47]
	s_nop 0
	v_fmac_f32_e32 v52, v36, v36
	v_fmac_f32_e32 v52, v37, v37
	v_pk_fma_f32 v[38:39], v[40:41], v[50:51], v[48:49]
	v_lshl_add_u64 v[40:41], v[128:129], 0, s[46:47]
	v_fmac_f32_e32 v52, v38, v38
	v_fmac_f32_e32 v52, v39, v39
	ds_bpermute_b32 v34, v118, v52
	global_store_dwordx4 v[40:41], v[36:39], off offset:64
	s_waitcnt lgkmcnt(0)
	v_add_f32_e32 v34, v52, v34
	ds_bpermute_b32 v35, v114, v34
	v_cvt_pk_bf16_f32 v36, v36, v37
	v_cvt_pk_bf16_f32 v37, v38, v39
	global_store_dwordx2 v[42:43], v[36:37], off offset:32
	s_and_saveexec_b64 s[2:3], s[0:1]
	s_nop 0
	v_lshl_add_u64 v[36:37], v[140:141], 2, s[4:5]
	s_waitcnt lgkmcnt(0)
	v_add_f32_e32 v34, v34, v35
	global_atomic_add_f32 v[36:37], v34, off offset:576
.LBB0_243:
	s_or_b64 exec, exec, s[2:3]
	v_add_co_u32_e32 v34, vcc, 0x280000, v142
	v_mul_f32_e32 v40, 0xbfb8aa3b, v30
	s_waitcnt lgkmcnt(0)
	v_addc_co_u32_e32 v35, vcc, 0, v143, vcc
	s_nop 0
	v_mul_f32_e32 v41, 0xbfb8aa3b, v31
	v_mul_f32_e32 v32, 0xbfb8aa3b, v32
	v_mul_f32_e32 v33, 0xbfb8aa3b, v33
	v_exp_f32_e32 v40, v40
	v_exp_f32_e32 v41, v41
	v_exp_f32_e32 v32, v32
	v_exp_f32_e32 v33, v33
	v_add_f32_e32 v40, 1.0, v40
	v_add_f32_e32 v41, 1.0, v41
	v_add_f32_e32 v42, 1.0, v32
	v_add_f32_e32 v43, 1.0, v33
	s_mov_b32 s2, 0x280000
	v_rcp_f32_e32 v32, v40
	v_rcp_f32_e32 v33, v41
	v_rcp_f32_e32 v40, v42
	v_rcp_f32_e32 v41, v43
	v_add_co_u32_e32 v30, vcc, s2, v128
	s_mov_b32 s2, 0x140000
	s_nop 0
	v_addc_co_u32_e32 v31, vcc, 0, v129, vcc
	v_add_co_u32_e32 v42, vcc, s2, v126
	v_lshl_add_u64 v[38:39], v[142:143], 0, s[48:49]
	s_nop 0
	v_addc_co_u32_e32 v43, vcc, 0, v127, vcc
	v_mul_f32_e32 v18, 0xbfb8aa3b, v18
	v_mul_f32_e32 v19, 0xbfb8aa3b, v19
	v_exp_f32_e32 v18, v18
	v_exp_f32_e32 v19, v19
	v_mul_f32_e32 v20, 0xbfb8aa3b, v20
	v_mul_f32_e32 v21, 0xbfb8aa3b, v21
	v_exp_f32_e32 v20, v20
	v_exp_f32_e32 v21, v21
	v_add_f32_e32 v18, 1.0, v18
	v_add_f32_e32 v19, 1.0, v19
	v_rcp_f32_e32 v18, v18
	v_rcp_f32_e32 v19, v19
	v_add_f32_e32 v20, 1.0, v20
	v_add_f32_e32 v21, 1.0, v21
	s_mov_b64 s[2:3], 0x140000
	s_waitcnt vmcnt(33)
	v_mov_b64_e32 v[34:35], v[218:219]
	v_mov_b64_e32 v[36:37], v[220:221]
	v_pk_fma_f32 v[26:27], v[26:27], v[32:33], v[34:35]
	v_pk_fma_f32 v[28:29], v[28:29], v[40:41], v[36:37]
	global_store_dwordx4 v[30:31], v[26:29], off
	v_cvt_pk_bf16_f32 v30, v26, v27
	v_cvt_pk_bf16_f32 v31, v28, v29
	global_store_dwordx2 v[42:43], v[30:31], off
	s_nop 0
	v_fma_f32 v36, v26, v26, 0
	v_rcp_f32_e32 v34, v20
	v_rcp_f32_e32 v35, v21
	v_fmac_f32_e32 v36, v27, v27
	v_fmac_f32_e32 v36, v28, v28
	v_fmac_f32_e32 v36, v29, v29
	v_lshl_add_u64 v[26:27], v[126:127], 0, s[2:3]
	s_waitcnt vmcnt(34)
	v_mov_b64_e32 v[30:31], v[222:223]
	v_mov_b64_e32 v[32:33], v[224:225]
	v_pk_fma_f32 v[20:21], v[22:23], v[18:19], v[30:31]
	s_nop 0
	v_fmac_f32_e32 v36, v20, v20
	v_fmac_f32_e32 v36, v21, v21
	v_pk_fma_f32 v[22:23], v[24:25], v[34:35], v[32:33]
	v_lshl_add_u64 v[24:25], v[128:129], 0, s[48:49]
	v_fmac_f32_e32 v36, v22, v22
	v_fmac_f32_e32 v36, v23, v23
	ds_bpermute_b32 v18, v118, v36
	global_store_dwordx4 v[24:25], v[20:23], off offset:64
	s_waitcnt lgkmcnt(0)
	v_add_f32_e32 v18, v36, v18
	ds_bpermute_b32 v19, v114, v18
	v_cvt_pk_bf16_f32 v20, v20, v21
	v_cvt_pk_bf16_f32 v21, v22, v23
	global_store_dwordx2 v[26:27], v[20:21], off offset:32
	s_and_saveexec_b64 s[2:3], s[0:1]
	s_nop 0
	v_lshl_add_u64 v[20:21], v[140:141], 2, s[4:5]
	s_waitcnt lgkmcnt(0)
	v_add_f32_e32 v18, v18, v19
	global_atomic_add_f32 v[20:21], v18, off offset:640
.LBB0_245:
	s_or_b64 exec, exec, s[2:3]
	v_add_co_u32_e32 v18, vcc, 0x2c0000, v142
	v_mul_f32_e32 v24, 0xbfb8aa3b, v14
	s_waitcnt lgkmcnt(0)
	v_addc_co_u32_e32 v19, vcc, 0, v143, vcc
	s_nop 0
	v_mul_f32_e32 v25, 0xbfb8aa3b, v15
	v_mul_f32_e32 v16, 0xbfb8aa3b, v16
	v_mul_f32_e32 v17, 0xbfb8aa3b, v17
	v_exp_f32_e32 v24, v24
	v_exp_f32_e32 v25, v25
	v_exp_f32_e32 v16, v16
	v_exp_f32_e32 v17, v17
	v_add_f32_e32 v24, 1.0, v24
	v_add_f32_e32 v25, 1.0, v25
	v_add_f32_e32 v26, 1.0, v16
	v_add_f32_e32 v27, 1.0, v17
	s_mov_b32 s2, 0x2c0000
	v_rcp_f32_e32 v16, v24
	v_rcp_f32_e32 v17, v25
	v_rcp_f32_e32 v24, v26
	v_rcp_f32_e32 v25, v27
	v_add_co_u32_e32 v14, vcc, s2, v128
	s_mov_b32 s2, 0x160000
	s_nop 0
	v_addc_co_u32_e32 v15, vcc, 0, v129, vcc
	v_add_co_u32_e32 v26, vcc, s2, v126
	v_lshl_add_u64 v[22:23], v[142:143], 0, s[66:67]
	s_nop 0
	v_addc_co_u32_e32 v27, vcc, 0, v127, vcc
	v_mul_f32_e32 v2, 0xbfb8aa3b, v2
	v_mul_f32_e32 v3, 0xbfb8aa3b, v3
	v_exp_f32_e32 v2, v2
	v_exp_f32_e32 v3, v3
	v_mul_f32_e32 v4, 0xbfb8aa3b, v4
	v_mul_f32_e32 v5, 0xbfb8aa3b, v5
	v_exp_f32_e32 v4, v4
	v_exp_f32_e32 v5, v5
	v_add_f32_e32 v2, 1.0, v2
	v_add_f32_e32 v3, 1.0, v3
	v_rcp_f32_e32 v2, v2
	v_rcp_f32_e32 v3, v3
	v_add_f32_e32 v4, 1.0, v4
	v_add_f32_e32 v5, 1.0, v5
	s_mov_b64 s[2:3], 0x160000
	s_waitcnt vmcnt(36)
	v_mov_b64_e32 v[18:19], v[226:227]
	v_mov_b64_e32 v[20:21], v[228:229]
	v_pk_fma_f32 v[10:11], v[10:11], v[16:17], v[18:19]
	v_pk_fma_f32 v[12:13], v[12:13], v[24:25], v[20:21]
	global_store_dwordx4 v[14:15], v[10:13], off
	v_cvt_pk_bf16_f32 v14, v10, v11
	v_cvt_pk_bf16_f32 v15, v12, v13
	global_store_dwordx2 v[26:27], v[14:15], off
	s_nop 0
	v_fma_f32 v20, v10, v10, 0
	v_rcp_f32_e32 v18, v4
	v_rcp_f32_e32 v19, v5
	v_fmac_f32_e32 v20, v11, v11
	v_fmac_f32_e32 v20, v12, v12
	v_fmac_f32_e32 v20, v13, v13
	v_lshl_add_u64 v[10:11], v[126:127], 0, s[2:3]
	s_waitcnt vmcnt(37)
	v_mov_b64_e32 v[14:15], v[230:231]
	v_mov_b64_e32 v[16:17], v[232:233]
	v_pk_fma_f32 v[4:5], v[6:7], v[2:3], v[14:15]
	s_nop 0
	v_fmac_f32_e32 v20, v4, v4
	v_fmac_f32_e32 v20, v5, v5
	v_pk_fma_f32 v[6:7], v[8:9], v[18:19], v[16:17]
	v_lshl_add_u64 v[8:9], v[128:129], 0, s[66:67]
	v_fmac_f32_e32 v20, v6, v6
	v_fmac_f32_e32 v20, v7, v7
	ds_bpermute_b32 v2, v118, v20
	global_store_dwordx4 v[8:9], v[4:7], off offset:64
	s_waitcnt lgkmcnt(0)
	v_add_f32_e32 v2, v20, v2
	ds_bpermute_b32 v3, v114, v2
	v_cvt_pk_bf16_f32 v4, v4, v5
	v_cvt_pk_bf16_f32 v5, v6, v7
	global_store_dwordx2 v[10:11], v[4:5], off offset:32
	s_and_saveexec_b64 s[2:3], s[0:1]
	s_cbranch_execz .LBB0_247
	v_lshl_add_u64 v[4:5], v[140:141], 2, s[4:5]
	s_waitcnt lgkmcnt(0)
	v_add_f32_e32 v2, v2, v3
	global_atomic_add_f32 v[4:5], v2, off offset:704
